# grid barrier: the L1 acquire-invalidate is issued at arrival (workgroup parked, one workgroup per CU) instead of after the release is observed
# speedup vs baseline: 1.0166x; 1.0068x over previous
.LBB0_47:
	s_or_b64 exec, exec, s[10:11]
	v_cvt_f32_u32_e32 v4, v2
	s_waitcnt vmcnt(0)
	v_readfirstlane_b32 s8, v3
	buffer_inv sc1
	v_sub_u32_e32 v3, 0, v2
	v_rcp_iflag_f32_e32 v4, v4
	v_add_u32_e32 v5, s8, v1
	v_mul_f32_e32 v4, 0x4f7ffffe, v4
	v_cvt_u32_f32_e32 v4, v4
	v_mul_lo_u32 v1, v3, v4
	v_mul_hi_u32 v1, v4, v1
	v_add_u32_e32 v1, v4, v1
	v_mul_hi_u32 v1, v5, v1
	v_mul_lo_u32 v3, v1, v2
	v_sub_u32_e32 v3, v5, v3
	v_add_u32_e32 v4, 1, v1
	v_cmp_ge_u32_e32 vcc, v3, v2
	s_nop 1
	v_cndmask_b32_e32 v1, v1, v4, vcc
	v_sub_u32_e32 v4, v3, v2
	v_cndmask_b32_e32 v3, v3, v4, vcc
	v_add_u32_e32 v4, 1, v1
	v_cmp_ge_u32_e32 vcc, v3, v2
	v_add_u32_e32 v3, 1, v5
	s_nop 0
	v_cndmask_b32_e32 v1, v1, v4, vcc
	v_mul_lo_u32 v4, v2, v1
	v_add_u32_e32 v2, v4, v2
	v_cmp_ne_u32_e32 vcc, v3, v2
	s_and_saveexec_b64 s[8:9], vcc
	s_xor_b64 s[8:9], exec, s[8:9]
	s_cbranch_execz .LBB0_61
	s_waitcnt lgkmcnt(0)
	v_mov_b32_e32 v0, 0x2000
	global_load_dword v0, v0, s[6:7] offset:1024 sc1
	s_add_u32 s14, s6, 0x2400
	s_addc_u32 s15, s7, 0
	s_waitcnt vmcnt(0)
	v_cmp_eq_u32_e32 vcc, v0, v1
	s_and_saveexec_b64 s[10:11], vcc
	s_cbranch_execz .LBB0_60
	s_add_u32 s12, s54, 0x68200
	s_addc_u32 s13, s55, 0
	s_mov_b32 s26, 1
	s_mov_b64 s[16:17], 0
	v_mov_b32_e32 v0, 0
	s_branch .LBB0_51

.LBB0_60:
	s_or_b64 exec, exec, s[10:11]
	s_waitcnt vmcnt(0)
	s_waitcnt vmcnt(0)

.LBB0_78:
	s_or_b64 exec, exec, s[8:9]
	s_mov_b64 s[8:9], exec
	v_mbcnt_lo_u32_b32 v0, s8, 0
	v_mbcnt_hi_u32_b32 v0, s9, v0
	v_cmp_eq_u32_e32 vcc, 0, v0
	s_waitcnt vmcnt(0)
	s_and_saveexec_b64 s[10:11], vcc
	s_cbranch_execz .LBB0_80
	s_bcnt1_i32_b64 s8, s[8:9]
	v_mov_b32_e32 v0, 0x2000
	v_mov_b32_e32 v1, s8
	global_atomic_add v0, v1, s[6:7] offset:1024

.LBB0_202:
	s_or_b64 exec, exec, s[8:9]
	v_cvt_f32_u32_e32 v4, v2
	s_waitcnt vmcnt(0)
	v_readfirstlane_b32 s6, v3
	buffer_inv sc1
	v_sub_u32_e32 v3, 0, v2
	v_rcp_iflag_f32_e32 v4, v4
	v_add_u32_e32 v5, s6, v1
	v_mul_f32_e32 v4, 0x4f7ffffe, v4
	v_cvt_u32_f32_e32 v4, v4
	v_mul_lo_u32 v1, v3, v4
	v_mul_hi_u32 v1, v4, v1
	v_add_u32_e32 v1, v4, v1
	v_mul_hi_u32 v1, v5, v1
	v_mul_lo_u32 v3, v1, v2
	v_sub_u32_e32 v3, v5, v3
	v_add_u32_e32 v4, 1, v1
	v_cmp_ge_u32_e32 vcc, v3, v2
	s_nop 1
	v_cndmask_b32_e32 v1, v1, v4, vcc
	v_sub_u32_e32 v4, v3, v2
	v_cndmask_b32_e32 v3, v3, v4, vcc
	v_add_u32_e32 v4, 1, v1
	v_cmp_ge_u32_e32 vcc, v3, v2
	v_add_u32_e32 v3, 1, v5
	s_nop 0
	v_cndmask_b32_e32 v1, v1, v4, vcc
	v_mul_lo_u32 v4, v2, v1
	v_add_u32_e32 v2, v4, v2
	v_cmp_ne_u32_e32 vcc, v3, v2
	s_and_saveexec_b64 s[6:7], vcc
	s_xor_b64 s[6:7], exec, s[6:7]
	s_cbranch_execz .LBB0_216
	s_waitcnt lgkmcnt(0)
	v_mov_b32_e32 v0, 0x2000
	global_load_dword v0, v0, s[4:5] offset:1024 sc1
	s_add_u32 s12, s4, 0x2400
	s_addc_u32 s13, s5, 0
	s_waitcnt vmcnt(0)
	v_cmp_eq_u32_e32 vcc, v0, v1
	s_and_saveexec_b64 s[8:9], vcc
	s_cbranch_execz .LBB0_215
	s_add_u32 s10, s54, 0x68200
	s_addc_u32 s11, s55, 0
	s_mov_b32 s24, 1
	s_mov_b64 s[14:15], 0
	v_mov_b32_e32 v0, 0
	s_branch .LBB0_206

.LBB0_215:
	s_or_b64 exec, exec, s[8:9]
	s_waitcnt vmcnt(0)
	s_waitcnt vmcnt(0)

.LBB0_233:
	s_or_b64 exec, exec, s[6:7]
	s_mov_b64 s[6:7], exec
	v_mbcnt_lo_u32_b32 v0, s6, 0
	v_mbcnt_hi_u32_b32 v0, s7, v0
	v_cmp_eq_u32_e32 vcc, 0, v0
	s_waitcnt vmcnt(0)
	s_and_saveexec_b64 s[8:9], vcc
	s_cbranch_execz .LBB0_235
	s_bcnt1_i32_b64 s6, s[6:7]
	v_mov_b32_e32 v0, 0x2000
	v_mov_b32_e32 v1, s6
	global_atomic_add v0, v1, s[4:5] offset:1024

.LBB0_1051:
	s_or_b64 exec, exec, s[6:7]
	v_cvt_f32_u32_e32 v4, v2
	s_waitcnt vmcnt(0)
	v_readfirstlane_b32 s4, v3
	buffer_inv sc1
	v_sub_u32_e32 v3, 0, v2
	v_rcp_iflag_f32_e32 v4, v4
	v_add_u32_e32 v5, s4, v1
	v_mul_f32_e32 v4, 0x4f7ffffe, v4
	v_cvt_u32_f32_e32 v4, v4
	v_mul_lo_u32 v1, v3, v4
	v_mul_hi_u32 v1, v4, v1
	v_add_u32_e32 v1, v4, v1
	v_mul_hi_u32 v1, v5, v1
	v_mul_lo_u32 v3, v1, v2
	v_sub_u32_e32 v3, v5, v3
	v_add_u32_e32 v4, 1, v1
	v_cmp_ge_u32_e32 vcc, v3, v2
	s_nop 1
	v_cndmask_b32_e32 v1, v1, v4, vcc
	v_sub_u32_e32 v4, v3, v2
	v_cndmask_b32_e32 v3, v3, v4, vcc
	v_add_u32_e32 v4, 1, v1
	v_cmp_ge_u32_e32 vcc, v3, v2
	v_add_u32_e32 v3, 1, v5
	s_nop 0
	v_cndmask_b32_e32 v1, v1, v4, vcc
	v_mul_lo_u32 v4, v2, v1
	v_add_u32_e32 v2, v4, v2
	v_cmp_ne_u32_e32 vcc, v3, v2
	s_and_saveexec_b64 s[4:5], vcc
	s_xor_b64 s[4:5], exec, s[4:5]
	s_cbranch_execz .LBB0_1065
	s_waitcnt lgkmcnt(0)
	v_mov_b32_e32 v0, 0x2000
	global_load_dword v0, v0, s[2:3] offset:1024 sc1
	s_add_u32 s10, s2, 0x2400
	s_addc_u32 s11, s3, 0
	s_waitcnt vmcnt(0)
	v_cmp_eq_u32_e32 vcc, v0, v1
	s_and_saveexec_b64 s[6:7], vcc
	s_cbranch_execz .LBB0_1064
	s_add_u32 s8, s54, 0x68200
	s_addc_u32 s9, s55, 0
	s_mov_b32 s22, 1
	s_mov_b64 s[12:13], 0
	v_mov_b32_e32 v0, 0
	s_branch .LBB0_1055

.LBB0_1064:
	s_or_b64 exec, exec, s[6:7]
	s_waitcnt vmcnt(0)
	s_waitcnt vmcnt(0)

.LBB0_1082:
	s_or_b64 exec, exec, s[4:5]
	s_mov_b64 s[4:5], exec
	v_mbcnt_lo_u32_b32 v0, s4, 0
	v_mbcnt_hi_u32_b32 v0, s5, v0
	v_cmp_eq_u32_e32 vcc, 0, v0
	s_waitcnt vmcnt(0)
	s_and_saveexec_b64 s[6:7], vcc
	s_cbranch_execz .LBB0_1084
	s_bcnt1_i32_b64 s4, s[4:5]
	v_mov_b32_e32 v0, 0x2000
	v_mov_b32_e32 v1, s4
	global_atomic_add v0, v1, s[2:3] offset:1024
